# as best + D loops: waves 4-7 take the tile barrier before their last 2 QK MFMAs
# speedup vs baseline: 1.0009x; 1.0009x over previous
; #define SBAR() __builtin_amdgcn_sched_barrier(0)
; template <int S, bool RSM> __device__ __forceinline__ void fsm_step(f32x16& pc0, f32x16& pc1, float& ps, float& l_reg, bf16x8& pa0, bf16x8& pa1, bf16x8& pa2, bf16x8& pa3) {
;     if (S < 4) {
; #pragma unroll
;         for (int r = 0; r < 4; ++r) pc1[4 * S + r] = __builtin_amdgcn_exp2f(pc1[4 * S + r]); }
;     if (S == 4) { PK4X(pc0, 0, pa0); if (!RSM) ps = ((pc0[0] + pc0[1]) + (pc0[2] + pc0[3])) + ((pc0[4] + pc0[5]) + (pc0[6] + pc0[7])); }
;     if (S == 5) { PK4X(pc0, 8, pa1); if (!RSM) ps += ((pc0[8] + pc0[9]) + (pc0[10] + pc0[11])) + ((pc0[12] + pc0[13]) + (pc0[14] + pc0[15])); }
;     if (S == 6) { PK4X(pc1, 0, pa2); if (!RSM) ps += ((pc1[0] + pc1[1]) + (pc1[2] + pc1[3])) + ((pc1[4] + pc1[5]) + (pc1[6] + pc1[7])); }
;     if (S == 7 && RSM) PK4X(pc1, 8, pa3);
;     if (S == 7 && !RSM) { PK4X(pc1, 8, pa3); ps += ((pc1[8] + pc1[9]) + (pc1[10] + pc1[11])) + ((pc1[12] + pc1[13]) + (pc1[14] + pc1[15]));
;         auto rr = __builtin_amdgcn_permlane32_swap(__float_as_uint(ps), __float_as_uint(ps), false, false); l_reg += __uint_as_float(rr[0]) + __uint_as_float(rr[1]); }
; }
; template <int NQ, int I> __device__ __forceinline__ void krd_pair(bf16x8& f0, bf16x8& f1, int ka, const int (&kb1)[2], const int (&kb2)[2]) {
;     constexpr bool HAS1 = NQ >= 8; constexpr int SHM_K1 = HAS1 ? 16384 : 0, NP1 = HAS1 ? 8 : 0;
;     if (I < NP1) { const int a_ = ka + kb1[0] + (((I < 8 ? I : 0) ^ kb1[1]) << 5); f0 = lds_rd128<0>(a_); f1 = lds_rd128<8192>(a_); }
;     else { const int a_ = ka + kb2[0] + ((((I - NP1) & 3) ^ kb2[1]) << 5); f0 = lds_rd128<SHM_K1>(a_); f1 = lds_rd128<SHM_K1 + 4096>(a_); }
; }
; template <int NQ, int I> __device__ __forceinline__ void qk_slot(f32x16& pn0, f32x16& pn1, f32x16& pc0, f32x16& pc1, float& ps, float& l_reg, bf16x8& pa0, bf16x8& pa1, bf16x8& pa2, bf16x8& pa3, ...
;     constexpr int AH = 1, RING = AH + 1;
;     if (I + AH < NQ) krd_pair<NQ, (I + AH < NQ ? I + AH : 0)>(kf0[(I + AH) % RING], kf1[(I + AH) % RING], ka, kb1, kb2);
;     constexpr int LEFT = (NQ - 1 - I) < AH ? (NQ - 1 - I) : AH;
;     if (LEFT == 2) asm volatile("s_waitcnt lgkmcnt(4)" ::: "memory"); else if (LEFT == 1) asm volatile("s_waitcnt lgkmcnt(2)" ::: "memory"); else asm volatile("s_waitcnt lgkmcnt(0)" ::: "memory");
;     SBAR();
.LBB0_699:
	s_waitcnt lgkmcnt(0)
	s_waitcnt lgkmcnt(0)
	s_lshl_b32 s22, s73, 13
	v_add_u32_e32 v0, s22, v240
	v_add_u32_e32 v10, v0, v236
	ds_read_b128 v[2:5], v10 offset:0
	ds_read_b128 v[6:9], v10 offset:0x1000
	s_waitcnt lgkmcnt(2)
	v_mfma_f32_32x32x16_bf16 v[160:175], v[196:199], v[188:191], v[112:127]
	v_exp_f32_e32 v14, v128
	v_exp_f32_e32 v15, v129
	v_exp_f32_e32 v196, v130
	v_exp_f32_e32 v197, v131
	v_exp_f32_e32 v198, v132
	v_exp_f32_e32 v199, v133
	v_exp_f32_e32 v204, v134
	v_mfma_f32_32x32x16_bf16 v[144:159], v[192:195], v[188:191], v[112:127]
	v_exp_f32_e32 v205, v135
	v_add_u32_e32 v132, v0, v235
	ds_read_b128 v[10:13], v132 offset:0
	ds_read_b128 v[128:131], v132 offset:0x1000
	s_waitcnt lgkmcnt(2)
	v_mfma_f32_32x32x16_bf16 v[160:175], v[2:5], v[184:187], v[160:175]
	v_exp_f32_e32 v192, v136
	v_exp_f32_e32 v193, v137
	v_exp_f32_e32 v194, v138
	v_exp_f32_e32 v195, v139
	v_exp_f32_e32 v140, v140
	v_exp_f32_e32 v141, v141
	v_exp_f32_e32 v142, v142
	v_mfma_f32_32x32x16_bf16 v[144:159], v[6:9], v[184:187], v[144:159]
	v_exp_f32_e32 v143, v143
	v_add_u32_e32 v0, v0, v234
	ds_read_b128 v[132:135], v0 offset:0
	ds_read_b128 v[136:139], v0 offset:0x1000
	s_waitcnt lgkmcnt(2)
	v_mfma_f32_32x32x16_bf16 v[160:175], v[10:13], v[180:183], v[160:175]
	v_cvt_pk_bf16_f32 v6, v244, v252
	v_cvt_pk_bf16_f32 v7, v245, v253
	v_cvt_pk_bf16_f32 v8, v246, v200
	v_cvt_pk_bf16_f32 v9, v247, v201
	v_cvt_pk_bf16_f32 v2, v248, v202
	v_cvt_pk_bf16_f32 v3, v249, v203
	v_cvt_pk_bf16_f32 v4, v250, v225
	v_mfma_f32_32x32x16_bf16 v[144:159], v[128:131], v[180:183], v[144:159]
	v_cvt_pk_bf16_f32 v5, v243, v251
	s_waitcnt lgkmcnt(0)
	s_and_b64 vcc, exec, s[8:9]
	s_cbranch_vccnz .Lmy_g1slow_0
	s_cmpk_gt_u32 s57, 0xfc
	s_cbranch_scc1 .Lmy_g1slow_0
	s_mov_b64 s[20:21], -1
	s_lshl_b32 s20, s35, 14
	s_add_i32 m0, s81, s22
	s_addk_i32 s20, 0xc000
	s_cmp_gt_i32 s35, 0
	s_cselect_b32 s20, s20, 0xc000
	s_waitcnt vmcnt(3) lgkmcnt(0)
	s_barrier
	v_mfma_f32_32x32x16_bf16 v[160:175], v[132:135], v[176:179], v[160:175]
	v_cvt_pk_bf16_f32 v128, v14, v15
	v_cvt_pk_bf16_f32 v129, v196, v197
	v_cvt_pk_bf16_f32 v130, v198, v199
	v_cvt_pk_bf16_f32 v131, v204, v205
	v_cvt_pk_bf16_f32 v10, v192, v193
	v_cvt_pk_bf16_f32 v11, v194, v195
	v_cvt_pk_bf16_f32 v12, v140, v141
	v_mfma_f32_32x32x16_bf16 v[144:159], v[136:139], v[176:179], v[144:159]
	v_cvt_pk_bf16_f32 v13, v142, v143
	s_add_i32 s20, s63, s20
	s_branch .Lmy_r2d_0
.Lmy_g1slow_0:
	v_mfma_f32_32x32x16_bf16 v[160:175], v[132:135], v[176:179], v[160:175]
	v_cvt_pk_bf16_f32 v128, v14, v15
	v_cvt_pk_bf16_f32 v129, v196, v197
	v_cvt_pk_bf16_f32 v130, v198, v199
	v_cvt_pk_bf16_f32 v131, v204, v205
	v_cvt_pk_bf16_f32 v10, v192, v193
	v_cvt_pk_bf16_f32 v11, v194, v195
	v_cvt_pk_bf16_f32 v12, v140, v141
	v_mfma_f32_32x32x16_bf16 v[144:159], v[136:139], v[176:179], v[144:159]
	v_cvt_pk_bf16_f32 v13, v142, v143
	s_and_b64 vcc, exec, s[8:9]
	s_cbranch_vccnz .LBB0_704
	s_cmpk_gt_u32 s57, 0xfc
	s_mov_b64 s[20:21], -1
	s_cbranch_scc1 .LBB0_741
	s_andn2_b64 vcc, exec, s[20:21]
	s_cbranch_vccnz .LBB0_703

; #define SBAR() __builtin_amdgcn_sched_barrier(0)
; template <int S, bool RSM> __device__ __forceinline__ void fsm_step(f32x16& pc0, f32x16& pc1, float& ps, float& l_reg, bf16x8& pa0, bf16x8& pa1, bf16x8& pa2, bf16x8& pa3) {
;     if (S < 4) {
; #pragma unroll
;         for (int r = 0; r < 4; ++r) pc1[4 * S + r] = __builtin_amdgcn_exp2f(pc1[4 * S + r]); }
;     if (S == 4) { PK4X(pc0, 0, pa0); if (!RSM) ps = ((pc0[0] + pc0[1]) + (pc0[2] + pc0[3])) + ((pc0[4] + pc0[5]) + (pc0[6] + pc0[7])); }
;     if (S == 5) { PK4X(pc0, 8, pa1); if (!RSM) ps += ((pc0[8] + pc0[9]) + (pc0[10] + pc0[11])) + ((pc0[12] + pc0[13]) + (pc0[14] + pc0[15])); }
;     if (S == 6) { PK4X(pc1, 0, pa2); if (!RSM) ps += ((pc1[0] + pc1[1]) + (pc1[2] + pc1[3])) + ((pc1[4] + pc1[5]) + (pc1[6] + pc1[7])); }
;     if (S == 7 && RSM) PK4X(pc1, 8, pa3);
;     if (S == 7 && !RSM) { PK4X(pc1, 8, pa3); ps += ((pc1[8] + pc1[9]) + (pc1[10] + pc1[11])) + ((pc1[12] + pc1[13]) + (pc1[14] + pc1[15]));
;         auto rr = __builtin_amdgcn_permlane32_swap(__float_as_uint(ps), __float_as_uint(ps), false, false); l_reg += __uint_as_float(rr[0]) + __uint_as_float(rr[1]); }
; }
; template <int NQ, int I> __device__ __forceinline__ void krd_pair(bf16x8& f0, bf16x8& f1, int ka, const int (&kb1)[2], const int (&kb2)[2]) {
;     constexpr bool HAS1 = NQ >= 8; constexpr int SHM_K1 = HAS1 ? 16384 : 0, NP1 = HAS1 ? 8 : 0;
;     if (I < NP1) { const int a_ = ka + kb1[0] + (((I < 8 ? I : 0) ^ kb1[1]) << 5); f0 = lds_rd128<0>(a_); f1 = lds_rd128<8192>(a_); }
;     else { const int a_ = ka + kb2[0] + ((((I - NP1) & 3) ^ kb2[1]) << 5); f0 = lds_rd128<SHM_K1>(a_); f1 = lds_rd128<SHM_K1 + 4096>(a_); }
; }
; template <int NQ, int I> __device__ __forceinline__ void qk_slot(f32x16& pn0, f32x16& pn1, f32x16& pc0, f32x16& pc1, float& ps, float& l_reg, bf16x8& pa0, bf16x8& pa1, bf16x8& pa2, bf16x8& pa3, ...
;     constexpr int AH = 1, RING = AH + 1;
;     if (I + AH < NQ) krd_pair<NQ, (I + AH < NQ ? I + AH : 0)>(kf0[(I + AH) % RING], kf1[(I + AH) % RING], ka, kb1, kb2);
;     constexpr int LEFT = (NQ - 1 - I) < AH ? (NQ - 1 - I) : AH;
;     if (LEFT == 2) asm volatile("s_waitcnt lgkmcnt(4)" ::: "memory"); else if (LEFT == 1) asm volatile("s_waitcnt lgkmcnt(2)" ::: "memory"); else asm volatile("s_waitcnt lgkmcnt(0)" ::: "memory");
;     SBAR();
.LBB0_714:
	s_or_b64 exec, exec, s[22:23]
	s_add_i32 s22, s35, 1
	s_cmp_lt_i32 s35, 3
	s_cselect_b32 s35, s22, 0
	v_exp_f32_e32 v14, v160
	v_exp_f32_e32 v15, v161
	v_exp_f32_e32 v196, v162
	v_exp_f32_e32 v197, v163
	v_exp_f32_e32 v198, v164
	v_exp_f32_e32 v199, v165
	v_exp_f32_e32 v200, v166
	v_exp_f32_e32 v201, v167
	v_exp_f32_e32 v202, v168
	v_exp_f32_e32 v203, v169
	v_exp_f32_e32 v204, v170
	v_exp_f32_e32 v205, v171
	v_exp_f32_e32 v206, v172
	v_exp_f32_e32 v207, v173
	v_exp_f32_e32 v208, v174
	v_exp_f32_e32 v209, v175
	s_waitcnt lgkmcnt(0)
	s_waitcnt lgkmcnt(0)
	v_add_u32_e32 v210, s78, v240
	v_add_u32_e32 v128, v210, v236
	ds_read_b128 v[10:13], v128 offset:0
	ds_read_b128 v[192:195], v128 offset:0x1000
	s_waitcnt lgkmcnt(2)
	v_mfma_f32_32x32x16_bf16 v[160:175], v[6:9], v[188:191], v[112:127]
	v_exp_f32_e32 v211, v144
	v_exp_f32_e32 v225, v145
	v_exp_f32_e32 v244, v146
	v_exp_f32_e32 v245, v147
	v_exp_f32_e32 v148, v148
	v_exp_f32_e32 v149, v149
	v_exp_f32_e32 v150, v150
	v_mfma_f32_32x32x16_bf16 v[128:143], v[2:5], v[188:191], v[112:127]
	v_exp_f32_e32 v151, v151
	v_add_u32_e32 v144, v210, v235
	ds_read_b128 v[2:5], v144 offset:0
	ds_read_b128 v[6:9], v144 offset:0x1000
	s_waitcnt lgkmcnt(2)
	v_mfma_f32_32x32x16_bf16 v[160:175], v[10:13], v[184:187], v[160:175]
	v_exp_f32_e32 v152, v152
	v_exp_f32_e32 v153, v153
	v_exp_f32_e32 v154, v154
	v_exp_f32_e32 v155, v155
	v_exp_f32_e32 v156, v156
	v_exp_f32_e32 v157, v157
	v_exp_f32_e32 v158, v158
	v_mfma_f32_32x32x16_bf16 v[128:143], v[192:195], v[184:187], v[128:143]
	v_exp_f32_e32 v159, v159
	v_add_u32_e32 v192, v210, v234
	ds_read_b128 v[10:13], v192 offset:0
	ds_read_b128 v[144:147], v192 offset:0x1000
	s_waitcnt lgkmcnt(2)
	v_mfma_f32_32x32x16_bf16 v[160:175], v[2:5], v[180:183], v[160:175]
	v_mfma_f32_32x32x16_bf16 v[128:143], v[6:9], v[180:183], v[128:143]
	v_cvt_pk_bf16_f32 v6, v14, v15
	v_cvt_pk_bf16_f32 v7, v196, v197
	v_cvt_pk_bf16_f32 v8, v198, v199
	v_cvt_pk_bf16_f32 v9, v200, v201
	v_cvt_pk_bf16_f32 v2, v202, v203
	v_cvt_pk_bf16_f32 v3, v204, v205
	v_cvt_pk_bf16_f32 v4, v206, v207
	v_cvt_pk_bf16_f32 v5, v208, v209
	s_waitcnt lgkmcnt(0)
	s_and_b64 vcc, exec, s[8:9]
	s_cbranch_vccnz .Lmy_g1slow_1
	s_cmpk_gt_u32 s57, 0xfb
	s_cbranch_scc1 .Lmy_g1slow_1
	s_mov_b64 s[22:23], -1
	s_lshl_b32 s22, s35, 14
	s_add_i32 m0, s81, s78
	s_addk_i32 s22, 0xc000
	s_cmp_gt_i32 s35, 0
	s_cselect_b32 s22, s22, 0xc000
	s_waitcnt vmcnt(3) lgkmcnt(0)
	s_barrier
	v_mfma_f32_32x32x16_bf16 v[160:175], v[10:13], v[176:179], v[160:175]
	v_mfma_f32_32x32x16_bf16 v[128:143], v[144:147], v[176:179], v[128:143]
	v_cvt_pk_bf16_f32 v144, v211, v225
	v_cvt_pk_bf16_f32 v145, v244, v245
	v_cvt_pk_bf16_f32 v146, v148, v149
	v_cvt_pk_bf16_f32 v147, v150, v151
	v_cvt_pk_bf16_f32 v10, v152, v153
	v_cvt_pk_bf16_f32 v11, v154, v155
	v_cvt_pk_bf16_f32 v12, v156, v157
	v_cvt_pk_bf16_f32 v13, v158, v159
	s_add_i32 s22, s63, s22
	s_branch .Lmy_r2d_1
.Lmy_g1slow_1:
	v_mfma_f32_32x32x16_bf16 v[160:175], v[10:13], v[176:179], v[160:175]
	v_mfma_f32_32x32x16_bf16 v[128:143], v[144:147], v[176:179], v[128:143]
	v_cvt_pk_bf16_f32 v144, v211, v225
	v_cvt_pk_bf16_f32 v145, v244, v245
	v_cvt_pk_bf16_f32 v146, v148, v149
	v_cvt_pk_bf16_f32 v147, v150, v151
	v_cvt_pk_bf16_f32 v10, v152, v153
	v_cvt_pk_bf16_f32 v11, v154, v155
	v_cvt_pk_bf16_f32 v12, v156, v157
	v_cvt_pk_bf16_f32 v13, v158, v159
	s_and_b64 vcc, exec, s[8:9]
	s_cbranch_vccnz .LBB0_719
	s_cmpk_gt_u32 s57, 0xfb
	s_mov_b64 s[22:23], -1
	s_cbranch_scc1 .LBB0_751
	s_andn2_b64 vcc, exec, s[22:23]
	s_cbranch_vccnz .LBB0_718

; #define SBAR() __builtin_amdgcn_sched_barrier(0)
; template <int S, bool RSM> __device__ __forceinline__ void fsm_step(f32x16& pc0, f32x16& pc1, float& ps, float& l_reg, bf16x8& pa0, bf16x8& pa1, bf16x8& pa2, bf16x8& pa3) {
;     if (S < 4) {
; #pragma unroll
;         for (int r = 0; r < 4; ++r) pc1[4 * S + r] = __builtin_amdgcn_exp2f(pc1[4 * S + r]); }
;     if (S == 4) { PK4X(pc0, 0, pa0); if (!RSM) ps = ((pc0[0] + pc0[1]) + (pc0[2] + pc0[3])) + ((pc0[4] + pc0[5]) + (pc0[6] + pc0[7])); }
;     if (S == 5) { PK4X(pc0, 8, pa1); if (!RSM) ps += ((pc0[8] + pc0[9]) + (pc0[10] + pc0[11])) + ((pc0[12] + pc0[13]) + (pc0[14] + pc0[15])); }
;     if (S == 6) { PK4X(pc1, 0, pa2); if (!RSM) ps += ((pc1[0] + pc1[1]) + (pc1[2] + pc1[3])) + ((pc1[4] + pc1[5]) + (pc1[6] + pc1[7])); }
;     if (S == 7 && RSM) PK4X(pc1, 8, pa3);
;     if (S == 7 && !RSM) { PK4X(pc1, 8, pa3); ps += ((pc1[8] + pc1[9]) + (pc1[10] + pc1[11])) + ((pc1[12] + pc1[13]) + (pc1[14] + pc1[15]));
;         auto rr = __builtin_amdgcn_permlane32_swap(__float_as_uint(ps), __float_as_uint(ps), false, false); l_reg += __uint_as_float(rr[0]) + __uint_as_float(rr[1]); }
; }
; template <int NQ, int I> __device__ __forceinline__ void krd_pair(bf16x8& f0, bf16x8& f1, int ka, const int (&kb1)[2], const int (&kb2)[2]) {
;     constexpr bool HAS1 = NQ >= 8; constexpr int SHM_K1 = HAS1 ? 16384 : 0, NP1 = HAS1 ? 8 : 0;
;     if (I < NP1) { const int a_ = ka + kb1[0] + (((I < 8 ? I : 0) ^ kb1[1]) << 5); f0 = lds_rd128<0>(a_); f1 = lds_rd128<8192>(a_); }
;     else { const int a_ = ka + kb2[0] + ((((I - NP1) & 3) ^ kb2[1]) << 5); f0 = lds_rd128<SHM_K1>(a_); f1 = lds_rd128<SHM_K1 + 4096>(a_); }
; }
; template <int NQ, int I> __device__ __forceinline__ void qk_slot(f32x16& pn0, f32x16& pn1, f32x16& pc0, f32x16& pc1, float& ps, float& l_reg, bf16x8& pa0, bf16x8& pa1, bf16x8& pa2, bf16x8& pa3, ...
;     constexpr int AH = 1, RING = AH + 1;
;     if (I + AH < NQ) krd_pair<NQ, (I + AH < NQ ? I + AH : 0)>(kf0[(I + AH) % RING], kf1[(I + AH) % RING], ka, kb1, kb2);
;     constexpr int LEFT = (NQ - 1 - I) < AH ? (NQ - 1 - I) : AH;
;     if (LEFT == 2) asm volatile("s_waitcnt lgkmcnt(4)" ::: "memory"); else if (LEFT == 1) asm volatile("s_waitcnt lgkmcnt(2)" ::: "memory"); else asm volatile("s_waitcnt lgkmcnt(0)" ::: "memory");
;     SBAR();
.LBB0_774:
	s_waitcnt lgkmcnt(0)
	s_waitcnt lgkmcnt(0)
	s_lshl_b32 s14, s19, 13
	v_add_u32_e32 v0, s14, v212
	v_add_u32_e32 v10, v0, v197
	ds_read_b128 v[2:5], v10 offset:0
	ds_read_b128 v[6:9], v10 offset:0x1000
	s_waitcnt lgkmcnt(2)
	v_mfma_f32_32x32x16_bf16 v[144:159], v[180:183], v[172:175], v[96:111]
	v_exp_f32_e32 v14, v112
	v_exp_f32_e32 v15, v113
	v_exp_f32_e32 v180, v114
	v_exp_f32_e32 v181, v115
	v_exp_f32_e32 v182, v116
	v_exp_f32_e32 v183, v117
	v_exp_f32_e32 v204, v118
	v_mfma_f32_32x32x16_bf16 v[128:143], v[176:179], v[172:175], v[96:111]
	v_exp_f32_e32 v205, v119
	v_add_u32_e32 v116, v0, v196
	ds_read_b128 v[10:13], v116 offset:0
	ds_read_b128 v[112:115], v116 offset:0x1000
	s_waitcnt lgkmcnt(2)
	v_mfma_f32_32x32x16_bf16 v[144:159], v[2:5], v[164:167], v[144:159]
	v_exp_f32_e32 v176, v120
	v_exp_f32_e32 v177, v121
	v_exp_f32_e32 v178, v122
	v_exp_f32_e32 v179, v123
	v_exp_f32_e32 v124, v124
	v_exp_f32_e32 v125, v125
	v_exp_f32_e32 v126, v126
	v_mfma_f32_32x32x16_bf16 v[128:143], v[6:9], v[164:167], v[128:143]
	v_exp_f32_e32 v127, v127
	v_add_u32_e32 v0, v0, v195
	ds_read_b128 v[116:119], v0 offset:0
	ds_read_b128 v[120:123], v0 offset:0x1000
	s_waitcnt lgkmcnt(2)
	v_mfma_f32_32x32x16_bf16 v[144:159], v[10:13], v[168:171], v[144:159]
	v_cvt_pk_bf16_f32 v6, v201, v225
	v_cvt_pk_bf16_f32 v7, v202, v230
	v_cvt_pk_bf16_f32 v8, v203, v231
	v_cvt_pk_bf16_f32 v9, v214, v232
	v_cvt_pk_bf16_f32 v2, v215, v233
	v_cvt_pk_bf16_f32 v3, v216, v234
	v_cvt_pk_bf16_f32 v4, v217, v235
	v_mfma_f32_32x32x16_bf16 v[128:143], v[112:115], v[168:171], v[128:143]
	v_cvt_pk_bf16_f32 v5, v200, v236
	s_waitcnt lgkmcnt(0)
	s_and_b64 vcc, exec, s[8:9]
	s_cbranch_vccnz .Lmy_g1slow_2
	s_cmpk_gt_u32 s17, 0xfc
	s_cbranch_scc1 .Lmy_g1slow_2
	s_mov_b64 s[12:13], -1
	s_lshl_b32 s12, s18, 14
	s_add_i32 m0, s81, s14
	s_addk_i32 s12, 0xc000
	s_cmp_gt_i32 s18, 0
	s_cselect_b32 s12, s12, 0xc000
	s_waitcnt vmcnt(3) lgkmcnt(0)
	s_barrier
	v_mfma_f32_32x32x16_bf16 v[144:159], v[116:119], v[160:163], v[144:159]
	v_cvt_pk_bf16_f32 v112, v14, v15
	v_cvt_pk_bf16_f32 v113, v180, v181
	v_cvt_pk_bf16_f32 v114, v182, v183
	v_cvt_pk_bf16_f32 v115, v204, v205
	v_cvt_pk_bf16_f32 v10, v176, v177
	v_cvt_pk_bf16_f32 v11, v178, v179
	v_cvt_pk_bf16_f32 v12, v124, v125
	v_mfma_f32_32x32x16_bf16 v[128:143], v[120:123], v[160:163], v[128:143]
	v_cvt_pk_bf16_f32 v13, v126, v127
	s_add_i32 s12, s63, s12
	s_branch .Lmy_r2d_2
.Lmy_g1slow_2:
	v_mfma_f32_32x32x16_bf16 v[144:159], v[116:119], v[160:163], v[144:159]
	v_cvt_pk_bf16_f32 v112, v14, v15
	v_cvt_pk_bf16_f32 v113, v180, v181
	v_cvt_pk_bf16_f32 v114, v182, v183
	v_cvt_pk_bf16_f32 v115, v204, v205
	v_cvt_pk_bf16_f32 v10, v176, v177
	v_cvt_pk_bf16_f32 v11, v178, v179
	v_cvt_pk_bf16_f32 v12, v124, v125
	v_mfma_f32_32x32x16_bf16 v[128:143], v[120:123], v[160:163], v[128:143]
	v_cvt_pk_bf16_f32 v13, v126, v127
	s_and_b64 vcc, exec, s[8:9]
	s_cbranch_vccnz .LBB0_779
	s_cmpk_gt_u32 s17, 0xfc
	s_mov_b64 s[12:13], -1
	s_cbranch_scc1 .LBB0_816
	s_andn2_b64 vcc, exec, s[12:13]
	s_cbranch_vccnz .LBB0_778

; #define SBAR() __builtin_amdgcn_sched_barrier(0)
; template <int S, bool RSM> __device__ __forceinline__ void fsm_step(f32x16& pc0, f32x16& pc1, float& ps, float& l_reg, bf16x8& pa0, bf16x8& pa1, bf16x8& pa2, bf16x8& pa3) {
;     if (S < 4) {
; #pragma unroll
;         for (int r = 0; r < 4; ++r) pc1[4 * S + r] = __builtin_amdgcn_exp2f(pc1[4 * S + r]); }
;     if (S == 4) { PK4X(pc0, 0, pa0); if (!RSM) ps = ((pc0[0] + pc0[1]) + (pc0[2] + pc0[3])) + ((pc0[4] + pc0[5]) + (pc0[6] + pc0[7])); }
;     if (S == 5) { PK4X(pc0, 8, pa1); if (!RSM) ps += ((pc0[8] + pc0[9]) + (pc0[10] + pc0[11])) + ((pc0[12] + pc0[13]) + (pc0[14] + pc0[15])); }
;     if (S == 6) { PK4X(pc1, 0, pa2); if (!RSM) ps += ((pc1[0] + pc1[1]) + (pc1[2] + pc1[3])) + ((pc1[4] + pc1[5]) + (pc1[6] + pc1[7])); }
;     if (S == 7 && RSM) PK4X(pc1, 8, pa3);
;     if (S == 7 && !RSM) { PK4X(pc1, 8, pa3); ps += ((pc1[8] + pc1[9]) + (pc1[10] + pc1[11])) + ((pc1[12] + pc1[13]) + (pc1[14] + pc1[15]));
;         auto rr = __builtin_amdgcn_permlane32_swap(__float_as_uint(ps), __float_as_uint(ps), false, false); l_reg += __uint_as_float(rr[0]) + __uint_as_float(rr[1]); }
; }
; template <int NQ, int I> __device__ __forceinline__ void krd_pair(bf16x8& f0, bf16x8& f1, int ka, const int (&kb1)[2], const int (&kb2)[2]) {
;     constexpr bool HAS1 = NQ >= 8; constexpr int SHM_K1 = HAS1 ? 16384 : 0, NP1 = HAS1 ? 8 : 0;
;     if (I < NP1) { const int a_ = ka + kb1[0] + (((I < 8 ? I : 0) ^ kb1[1]) << 5); f0 = lds_rd128<0>(a_); f1 = lds_rd128<8192>(a_); }
;     else { const int a_ = ka + kb2[0] + ((((I - NP1) & 3) ^ kb2[1]) << 5); f0 = lds_rd128<SHM_K1>(a_); f1 = lds_rd128<SHM_K1 + 4096>(a_); }
; }
; template <int NQ, int I> __device__ __forceinline__ void qk_slot(f32x16& pn0, f32x16& pn1, f32x16& pc0, f32x16& pc1, float& ps, float& l_reg, bf16x8& pa0, bf16x8& pa1, bf16x8& pa2, bf16x8& pa3, ...
;     constexpr int AH = 1, RING = AH + 1;
;     if (I + AH < NQ) krd_pair<NQ, (I + AH < NQ ? I + AH : 0)>(kf0[(I + AH) % RING], kf1[(I + AH) % RING], ka, kb1, kb2);
;     constexpr int LEFT = (NQ - 1 - I) < AH ? (NQ - 1 - I) : AH;
;     if (LEFT == 2) asm volatile("s_waitcnt lgkmcnt(4)" ::: "memory"); else if (LEFT == 1) asm volatile("s_waitcnt lgkmcnt(2)" ::: "memory"); else asm volatile("s_waitcnt lgkmcnt(0)" ::: "memory");
;     SBAR();
.LBB0_789:
	s_or_b64 exec, exec, s[14:15]
	s_add_i32 s14, s18, 1
	s_cmp_lt_i32 s18, 3
	s_cselect_b32 s18, s14, 0
	v_exp_f32_e32 v14, v144
	v_exp_f32_e32 v15, v145
	v_exp_f32_e32 v180, v146
	v_exp_f32_e32 v181, v147
	v_exp_f32_e32 v182, v148
	v_exp_f32_e32 v183, v149
	v_exp_f32_e32 v200, v150
	v_exp_f32_e32 v201, v151
	v_exp_f32_e32 v202, v152
	v_exp_f32_e32 v203, v153
	v_exp_f32_e32 v204, v154
	v_exp_f32_e32 v205, v155
	v_exp_f32_e32 v206, v156
	v_exp_f32_e32 v207, v157
	v_exp_f32_e32 v208, v158
	v_exp_f32_e32 v209, v159
	s_waitcnt lgkmcnt(0)
	s_waitcnt lgkmcnt(0)
	v_add_u32_e32 v210, s26, v212
	v_add_u32_e32 v112, v210, v197
	ds_read_b128 v[10:13], v112 offset:0
	ds_read_b128 v[176:179], v112 offset:0x1000
	s_waitcnt lgkmcnt(2)
	v_mfma_f32_32x32x16_bf16 v[144:159], v[6:9], v[172:175], v[96:111]
	v_exp_f32_e32 v211, v128
	v_exp_f32_e32 v215, v129
	v_exp_f32_e32 v216, v130
	v_exp_f32_e32 v217, v131
	v_exp_f32_e32 v132, v132
	v_exp_f32_e32 v133, v133
	v_exp_f32_e32 v134, v134
	v_mfma_f32_32x32x16_bf16 v[112:127], v[2:5], v[172:175], v[96:111]
	v_exp_f32_e32 v135, v135
	v_add_u32_e32 v128, v210, v196
	ds_read_b128 v[2:5], v128 offset:0
	ds_read_b128 v[6:9], v128 offset:0x1000
	s_waitcnt lgkmcnt(2)
	v_mfma_f32_32x32x16_bf16 v[144:159], v[10:13], v[164:167], v[144:159]
	v_exp_f32_e32 v136, v136
	v_exp_f32_e32 v137, v137
	v_exp_f32_e32 v138, v138
	v_exp_f32_e32 v139, v139
	v_exp_f32_e32 v140, v140
	v_exp_f32_e32 v141, v141
	v_exp_f32_e32 v142, v142
	v_mfma_f32_32x32x16_bf16 v[112:127], v[176:179], v[164:167], v[112:127]
	v_exp_f32_e32 v143, v143
	v_add_u32_e32 v176, v210, v195
	ds_read_b128 v[10:13], v176 offset:0
	ds_read_b128 v[128:131], v176 offset:0x1000
	s_waitcnt lgkmcnt(2)
	v_mfma_f32_32x32x16_bf16 v[144:159], v[2:5], v[168:171], v[144:159]
	v_mfma_f32_32x32x16_bf16 v[112:127], v[6:9], v[168:171], v[112:127]
	v_cvt_pk_bf16_f32 v6, v14, v15
	v_cvt_pk_bf16_f32 v7, v180, v181
	v_cvt_pk_bf16_f32 v8, v182, v183
	v_cvt_pk_bf16_f32 v9, v200, v201
	v_cvt_pk_bf16_f32 v2, v202, v203
	v_cvt_pk_bf16_f32 v3, v204, v205
	v_cvt_pk_bf16_f32 v4, v206, v207
	v_cvt_pk_bf16_f32 v5, v208, v209
	s_waitcnt lgkmcnt(0)
	s_and_b64 vcc, exec, s[8:9]
	s_cbranch_vccnz .Lmy_g1slow_3
	s_cmpk_gt_u32 s17, 0xfb
	s_cbranch_scc1 .Lmy_g1slow_3
	s_mov_b64 s[14:15], -1
	s_lshl_b32 s14, s18, 14
	s_add_i32 m0, s81, s26
	s_addk_i32 s14, 0xc000
	s_cmp_gt_i32 s18, 0
	s_cselect_b32 s14, s14, 0xc000
	s_waitcnt vmcnt(3) lgkmcnt(0)
	s_barrier
	v_mfma_f32_32x32x16_bf16 v[144:159], v[10:13], v[160:163], v[144:159]
	v_mfma_f32_32x32x16_bf16 v[112:127], v[128:131], v[160:163], v[112:127]
	v_cvt_pk_bf16_f32 v128, v211, v215
	v_cvt_pk_bf16_f32 v129, v216, v217
	v_cvt_pk_bf16_f32 v130, v132, v133
	v_cvt_pk_bf16_f32 v131, v134, v135
	v_cvt_pk_bf16_f32 v10, v136, v137
	v_cvt_pk_bf16_f32 v11, v138, v139
	v_cvt_pk_bf16_f32 v12, v140, v141
	v_cvt_pk_bf16_f32 v13, v142, v143
	s_add_i32 s14, s63, s14
	s_branch .Lmy_r2d_3
.Lmy_g1slow_3:
	v_mfma_f32_32x32x16_bf16 v[144:159], v[10:13], v[160:163], v[144:159]
	v_mfma_f32_32x32x16_bf16 v[112:127], v[128:131], v[160:163], v[112:127]
	v_cvt_pk_bf16_f32 v128, v211, v215
	v_cvt_pk_bf16_f32 v129, v216, v217
	v_cvt_pk_bf16_f32 v130, v132, v133
	v_cvt_pk_bf16_f32 v131, v134, v135
	v_cvt_pk_bf16_f32 v10, v136, v137
	v_cvt_pk_bf16_f32 v11, v138, v139
	v_cvt_pk_bf16_f32 v12, v140, v141
	v_cvt_pk_bf16_f32 v13, v142, v143
	s_and_b64 vcc, exec, s[8:9]
	s_cbranch_vccnz .LBB0_794
	s_cmpk_gt_u32 s17, 0xfb
	s_mov_b64 s[14:15], -1
	s_cbranch_scc1 .LBB0_826
	s_andn2_b64 vcc, exec, s[14:15]
	s_cbranch_vccnz .LBB0_793
